# removed the grid barrier between the GLU phase and GLA pass A (no dependency); attention q/k prep moved behind the next barrier (start of GLA pass B)
# speedup vs baseline: 1.0062x; 1.0016x over previous
.LBB0_1054:
	s_waitcnt vmcnt(0)
	s_barrier
	s_mov_b64 s[28:29], s[66:67]
	s_waitcnt lgkmcnt(0)
	s_barrier
	s_mov_b64 s[0:1], s[68:69]
	v_mov_b32_e32 v36, v194
	s_add_u32 s26, s28, 0x5800000
	v_cndmask_b32_e64 v0, 0, 1, s[14:15]
	s_mov_b32 s40, s64
	v_readfirstlane_b32 s41, v36
	s_addc_u32 s27, s29, 0
	v_cmp_ne_u32_e64 s[12:13], 1, v0
	s_andn2_b64 vcc, exec, s[14:15]
	v_and_b32_e32 v39, 15, v36
	s_cbranch_vccnz .LBB0_1108
	v_and_b32_e32 v10, 15, v36
	s_cbranch_execz .LBB0_1109
	s_branch .LBB0_1118

.LBB0_1117:
	v_mov_b32_e32 v10, v39
.LBB0_1118:
.LBB0_1121:
	s_getreg_b32 s6, hwreg(HW_REG_XCC_ID, 0, 4)
	s_waitcnt vmcnt(0)
	s_barrier
	s_and_saveexec_b64 s[0:1], s[46:47]
	s_cbranch_execz .LBB0_1173
	s_add_i32 s7, 0, 0x20160
	v_mov_b32_e32 v0, s7
	s_waitcnt vmcnt(0) expcnt(0) lgkmcnt(0)
	ds_read_b32 v2, v0
	s_add_i32 s7, 0, 0x20164
	v_mov_b32_e32 v0, s7
	ds_read_b32 v0, v0
	s_and_b32 s51, s6, 15
	s_waitcnt lgkmcnt(1)
	v_cmp_ne_u32_e32 vcc, 0, v2
	s_cbranch_vccnz .LBB0_1137
	s_add_u32 s6, s66, 0x1200
	s_addc_u32 s7, s67, 0
	s_add_u32 s14, s66, 0x1400
	s_addc_u32 s15, s67, 0
	s_add_u32 s16, s66, 0x1500
	s_addc_u32 s17, s67, 0
	s_add_u32 s18, s66, 0x1600
	s_addc_u32 s19, s67, 0
	s_add_u32 s20, s66, 0x1700
	s_addc_u32 s21, s67, 0
	s_add_u32 s22, s66, 0x1800
	s_addc_u32 s23, s67, 0
	s_add_u32 s24, s66, 0x1900
	s_addc_u32 s25, s67, 0
	s_add_u32 s26, s66, 0x1a00
	s_addc_u32 s27, s67, 0
	s_add_u32 s28, s66, 0x1b00
	s_addc_u32 s29, s67, 0
	s_add_u32 s30, s66, 0x1c00
	s_addc_u32 s31, s67, 0
	s_add_u32 s34, s66, 0x1d00
	s_addc_u32 s35, s67, 0
	s_add_u32 s36, s66, 0x1e00
	s_addc_u32 s37, s67, 0
	s_add_u32 s38, s66, 0x1f00
	s_addc_u32 s39, s67, 0
	s_add_u32 s40, s66, 0x2000
	s_addc_u32 s41, s67, 0
	s_add_u32 s42, s66, 0x2100
	s_addc_u32 s43, s67, 0
	s_add_u32 s44, s66, 0x2200
	s_addc_u32 s45, s67, 0
	s_mul_i32 s72, s65, s74
	s_add_u32 s58, s66, 0x2300
	s_mul_i32 s72, s72, s64
	s_addc_u32 s59, s67, 0
	s_mov_b32 s73, 1
	v_mov_b32_e32 v16, 0
	s_branch .LBB0_1125

.LBB0_1173:
	s_or_b64 exec, exec, s[0:1]
	s_barrier
	v_lshrrev_b32_e32 v0, 6, v194
	s_lshl_b32 s23, s64, 3
	v_readfirstlane_b32 s22, v0
	s_lshl_b32 s24, s2, 3
	s_add_i32 s22, s22, s24
	s_cmp_lt_u32 s22, 0x2000
	s_cbranch_scc0 .Lprep_done_L0
	s_add_u32 s0, s66, 0x8000
	s_addc_u32 s1, s67, 0
	s_add_u32 s6, s66, 0x5801000
	s_addc_u32 s7, s67, 0
	v_and_b32_e32 v0, 63, v194
	v_mov_b32_e32 v11, 0
	v_and_b32_e32 v1, 15, v0
	v_lshlrev_b32_e32 v2, 3, v0
	v_add_u32_e32 v3, 0x1800, v2
	v_cmp_lt_u32_e32 vcc, 31, v0
	v_mov_b32_e32 v20, 0x1700
	s_nop 1
	v_cndmask_b32_e32 v20, 0, v20, vcc
	v_add_u32_e32 v4, v2, v20
	v_and_b32_e32 v21, 4, v1
	v_cmp_ne_u32_e32 vcc, 0, v21
	v_mov_b32_e32 v22, 1.0
	v_mov_b32_e32 v5, -1.0
	v_cndmask_b32_e32 v5, v5, v22, vcc
	v_mov_b32_e32 v6, 0x358637bd
	v_cmp_gt_u32_e32 vcc, 8, v1
	s_nop 1
	v_cndmask_b32_e64 v7, 0, 1, vcc
	v_mov_b32_e32 v22, 0x80
	v_cndmask_b32_e32 v8, v22, v11, vcc
	v_cmp_lt_u32_e32 vcc, 31, v0
	s_nop 1
	v_cndmask_b32_e32 v9, 0, v8, vcc
	v_and_b32_e32 v10, 3, v1
	v_lshlrev_b32_e32 v10, 5, v10
	global_load_dwordx4 v[24:27], v11, s[66:67] offset:152
	v_lshlrev_b32_e32 v20, 4, v1
	v_mov_b32_e32 v21, 0
	s_waitcnt vmcnt(0)
	v_lshl_add_u64 v[24:25], v[24:25], 0, v[20:21]
	v_lshl_add_u64 v[26:27], v[26:27], 0, v[20:21]
	global_load_dwordx4 v[12:15], v[24:25], off
	global_load_dwordx4 v[16:19], v[26:27], off

.Lprep_done_L0:
	s_mov_b64 s[58:59], s[66:67]
	s_mov_b64 s[0:1], s[68:69]
	s_waitcnt lgkmcnt(0)
	v_mov_b32_e32 v0, v194
	s_mov_b32 s51, s64
	s_and_b64 vcc, exec, s[4:5]
	s_barrier
	s_cbranch_vccnz .LBB0_1188
	v_ashrrev_i32_e32 v1, 6, v0
	v_mov_b32_e32 v43, 0
	v_bfe_u32 v5, v0, 4, 2
	s_movk_i32 s0, 0x1100
	v_lshlrev_b32_e32 v46, 4, v5
	v_mov_b32_e32 v47, v43
	v_lshlrev_b32_e32 v50, 4, v1
	v_mul_lo_u32 v4, v1, s0
	v_and_b32_e32 v41, 15, v0
	v_lshl_add_u64 v[2:3], s[58:59], 0, v[46:47]
	s_mov_b64 s[0:1], 0x10a00000
	v_ashrrev_i32_e32 v51, 31, v50
	v_lshl_add_u64 v[48:49], v[2:3], 0, s[0:1]
	v_lshl_add_u64 v[2:3], v[50:51], 1, s[58:59]
	v_lshlrev_b32_e32 v42, 1, v41
	s_add_u32 s60, s58, 0x5800000
	v_and_b32_e32 v40, 0x7f, v0
	v_lshl_add_u64 v[2:3], v[2:3], 0, v[42:43]
	s_mov_b64 s[0:1], 0xe800000
	s_addc_u32 s61, s59, 0
	v_ashrrev_i32_e32 v6, 7, v0
	v_lshl_add_u64 v[52:53], v[2:3], 0, s[0:1]
	s_add_i32 s0, 0, 0x1f000
	v_lshlrev_b32_e32 v2, 2, v40
	s_add_i32 s14, 0, 0x11800
	s_movk_i32 s23, 0x880
	v_lshlrev_b32_e32 v45, 4, v6
	v_lshl_add_u32 v47, v0, 2, s0
	v_add_u32_e32 v55, s0, v2
	s_movk_i32 s0, 0x80
	v_mul_u32_u24_e32 v87, 0x110, v41
	s_add_i32 s22, 0, 0x11a00
	v_add_u32_e32 v89, s14, v2
	v_mul_lo_u32 v2, v6, s23
	v_cmp_gt_u32_e64 s[6:7], s0, v0
	s_movk_i32 s0, 0x110
	v_add3_u32 v88, 0, v4, v87
	v_or_b32_e32 v4, v45, v41
	v_add_u32_e32 v54, s22, v46
	v_or_b32_e32 v2, v2, v40
	v_mad_u64_u32 v[56:57], s[0:1], v4, s0, v[54:55]
	v_lshlrev_b32_e32 v2, 1, v2
	s_add_i32 s0, 0, 0x15e00
	v_add_u32_e32 v8, 0x110, v2
	v_add_u32_e32 v92, s22, v8
	v_add_u32_e32 v93, s0, v8
	v_add_u32_e32 v8, 0x220, v2
	v_add_u32_e32 v94, s22, v8
	v_add_u32_e32 v95, s0, v8
	v_add_u32_e32 v8, 0x330, v2
	v_add_u32_e32 v96, s22, v8
	v_add_u32_e32 v97, s0, v8
	v_add_u32_e32 v8, 0x440, v2
	v_add_u32_e32 v98, s22, v8
	v_add_u32_e32 v99, s0, v8
	v_add_u32_e32 v8, 0x550, v2
	v_add_u32_e32 v100, s22, v8
	v_add_u32_e32 v101, s0, v8
	v_add_u32_e32 v8, 0x660, v2
	v_add_u32_e32 v102, s22, v8
	v_add_u32_e32 v103, s0, v8
	v_add_u32_e32 v8, 0x770, v2
	v_add_u32_e32 v104, s22, v8
	v_add_u32_e32 v105, s0, v8
	v_add_u32_e32 v8, 0x880, v2
	v_add_u32_e32 v106, s22, v8
	v_add_u32_e32 v107, s0, v8
	v_add_u32_e32 v8, 0x990, v2
	v_add_u32_e32 v108, s22, v8
	v_add_u32_e32 v109, s0, v8
	v_add_u32_e32 v8, 0xaa0, v2
	v_add_u32_e32 v110, s22, v8
	v_add_u32_e32 v111, s0, v8
	v_add_u32_e32 v8, 0xbb0, v2
	v_add_u32_e32 v112, s22, v8
	v_add_u32_e32 v113, s0, v8
	v_add_u32_e32 v8, 0xcc0, v2
	v_mul_u32_u24_e32 v0, 0x48, v40
	v_lshlrev_b32_e32 v1, 1, v1
	v_add_u32_e32 v114, s22, v8
	v_add_u32_e32 v115, s0, v8
	v_add_u32_e32 v8, 0xdd0, v2
	v_lshlrev_b32_e32 v44, 2, v5
	v_lshlrev_b32_e32 v0, 1, v0
	v_lshlrev_b32_e32 v3, 5, v6
	v_and_b32_e32 v1, 2, v1
	v_add_u32_e32 v90, s22, v2
	v_add_u32_e32 v91, s0, v2
	v_add_u32_e32 v116, s22, v8
	v_add_u32_e32 v117, s0, v8
	v_add_u32_e32 v8, 0xee0, v2
	v_add_u32_e32 v2, 0xff0, v2
	v_add3_u32 v86, 0, v0, v3
	v_or_b32_e32 v3, v44, v45
	v_add_u32_e32 v120, s22, v2
	v_add_u32_e32 v121, s0, v2
	v_lshl_or_b32 v2, v1, 4, v41
	v_lshlrev_b32_e32 v0, 3, v5
	v_or_b32_e32 v5, v50, v41
	s_movk_i32 s1, 0x90
	s_add_i32 s38, 0, 0x1a200
	v_add_u32_e32 v118, s22, v8
	v_cmp_le_i32_e64 s[22:23], v1, v6
	v_or_b32_e32 v10, 1, v3
	v_or_b32_e32 v11, 2, v3
	v_or_b32_e32 v12, 3, v3
	v_cmp_lt_i32_e64 s[24:25], v1, v6
	v_or_b32_e32 v1, 16, v2
	v_mul_lo_u32 v5, v5, s1
	v_add_u32_e32 v119, s0, v8
	v_mul_u32_u24_e32 v8, 0x110, v2
	v_mul_lo_u32 v9, v3, s1
	v_or_b32_e32 v13, 16, v41
	v_lshl_add_u32 v14, v2, 1, s38
	v_cmp_gt_i32_e64 s[26:27], v2, v3
	v_cmp_gt_i32_e64 s[28:29], v2, v10
	v_cmp_gt_i32_e64 s[30:31], v2, v11
	v_cmp_gt_i32_e64 s[34:35], v2, v12
	v_lshlrev_b32_e32 v2, 1, v1
	v_add_u32_e32 v4, s0, v46
	v_add_u32_e32 v5, 0, v5
	v_add_u32_e32 v7, s38, v46
	v_add_u32_e32 v57, 0, v46
	v_cmp_lt_i32_e64 s[14:15], 0, v6
	v_cmp_lt_i32_e64 s[16:17], 1, v6
	v_cmp_lt_i32_e64 s[18:19], 2, v6
	v_cmp_lt_i32_e64 s[20:21], 3, v6
	v_mul_u32_u24_e32 v6, 0x90, v41
	v_mul_u32_u24_e32 v13, 0x110, v13
	v_add3_u32 v122, s38, v9, v2
	s_mov_b32 s63, 0
	v_cmp_gt_i32_e64 s[36:37], v1, v3
	v_cmp_gt_i32_e64 s[38:39], v1, v10
	v_add_u32_e32 v123, 0x90, v122
	v_cmp_gt_i32_e64 s[40:41], v1, v11
	v_add_u32_e32 v124, 0x120, v122
	v_cmp_gt_i32_e64 s[42:43], v1, v12
	v_add_u32_e32 v125, 0x1b0, v122
	v_sub_u32_e32 v126, 0, v44
	v_sub_u32_e32 v127, 0, v45
	s_movk_i32 s78, 0x1000
	s_movk_i32 s79, 0x2000
	s_movk_i32 s80, 0x3000
	s_movk_i32 s81, 0x4000
	s_movk_i32 s82, 0x5000
	s_movk_i32 s83, 0x6000
	s_movk_i32 s84, 0x7000
	s_mov_b32 s85, 0xc800000
	s_movk_i32 s86, 0x1800
	s_mov_b64 s[70:71], 0x1600
	s_mov_b32 s87, 0xffff0000
	s_mov_b32 s88, 0xbfb8aa3b
	s_mov_b32 s89, 0x800000
	s_mov_b32 s90, 0x3f317217
	s_mov_b32 s91, 0x7f800000
	s_movk_i32 s92, 0x7fff
	v_add_u32_e32 v128, v88, v0
	v_add_u32_e32 v129, v14, v9
	v_add_u32_e32 v130, v5, v46
	v_add_u32_e32 v131, v7, v6
	v_add_u32_e32 v132, v54, v13
	v_add_u32_e32 v133, v57, v6
	v_mov_b32_e32 v134, 0x41b17218
	v_mov_b32_e32 v135, 1
	v_add_u32_e32 v136, v4, v8
	s_mov_b32 s93, s2
	s_mov_b32 s94, s2
	s_branch .LBB0_1176

.LBB0_2664:
	s_waitcnt vmcnt(0)
	s_barrier
	s_mov_b64 s[24:25], s[66:67]
	s_waitcnt lgkmcnt(0)
	s_barrier
	s_mov_b64 s[0:1], s[68:69]
	v_mov_b32_e32 v36, v194
	s_add_u32 s22, s24, 0x5800000
	s_mov_b32 s36, s64
	v_readfirstlane_b32 s37, v36
	s_addc_u32 s23, s25, 0
	s_and_b64 vcc, exec, s[12:13]
	v_and_b32_e32 v39, 15, v36
	s_cbranch_vccnz .LBB0_2718
	v_and_b32_e32 v10, 15, v36
	s_cbranch_execz .LBB0_2719
	s_branch .LBB0_2728

.LBB0_2727:
	v_mov_b32_e32 v10, v39
.LBB0_2728:
.LBB0_2731:
	s_getreg_b32 s8, hwreg(HW_REG_XCC_ID, 0, 4)
	s_waitcnt vmcnt(0)
	s_barrier
	s_and_saveexec_b64 s[0:1], s[46:47]
	s_cbranch_execz .LBB0_2783
	s_add_i32 s9, 0, 0x20160
	v_mov_b32_e32 v0, s9
	s_waitcnt vmcnt(0) expcnt(0) lgkmcnt(0)
	ds_read_b32 v2, v0
	s_add_i32 s9, 0, 0x20164
	v_mov_b32_e32 v0, s9
	ds_read_b32 v0, v0
	s_and_b32 s52, s8, 15
	s_waitcnt lgkmcnt(1)
	v_cmp_ne_u32_e32 vcc, 0, v2
	s_cbranch_vccnz .LBB0_2747
	s_add_u32 s8, s66, 0x1200
	s_addc_u32 s9, s67, 0
	s_add_u32 s10, s66, 0x1400
	s_addc_u32 s11, s67, 0
	s_add_u32 s12, s66, 0x1500
	s_addc_u32 s13, s67, 0
	s_add_u32 s14, s66, 0x1600
	s_addc_u32 s15, s67, 0
	s_add_u32 s16, s66, 0x1700
	s_addc_u32 s17, s67, 0
	s_add_u32 s18, s66, 0x1800
	s_addc_u32 s19, s67, 0
	s_add_u32 s20, s66, 0x1900
	s_addc_u32 s21, s67, 0
	s_add_u32 s22, s66, 0x1a00
	s_addc_u32 s23, s67, 0
	s_add_u32 s24, s66, 0x1b00
	s_addc_u32 s25, s67, 0
	s_add_u32 s26, s66, 0x1c00
	s_addc_u32 s27, s67, 0
	s_add_u32 s28, s66, 0x1d00
	s_addc_u32 s29, s67, 0
	s_add_u32 s30, s66, 0x1e00
	s_addc_u32 s31, s67, 0
	s_add_u32 s34, s66, 0x1f00
	s_addc_u32 s35, s67, 0
	s_add_u32 s36, s66, 0x2000
	s_addc_u32 s37, s67, 0
	s_add_u32 s38, s66, 0x2100
	s_addc_u32 s39, s67, 0
	s_add_u32 s40, s66, 0x2200
	s_addc_u32 s41, s67, 0
	s_mul_i32 s53, s65, s74
	s_add_u32 s42, s66, 0x2300
	s_mul_i32 s53, s53, s64
	s_addc_u32 s43, s67, 0
	s_mov_b32 s54, 1
	v_mov_b32_e32 v16, 0
	s_branch .LBB0_2735

.LBB0_2783:
	s_or_b64 exec, exec, s[0:1]
	s_barrier
	v_lshrrev_b32_e32 v0, 6, v194
	s_lshl_b32 s19, s64, 3
	v_readfirstlane_b32 s18, v0
	s_lshl_b32 s20, s2, 3
	s_add_i32 s18, s18, s20
	s_cmp_lt_u32 s18, 0x2000
	s_cbranch_scc0 .Lprep_done_L1
	s_add_u32 s0, s66, 0x8000
	s_addc_u32 s1, s67, 0
	s_add_u32 s8, s66, 0x5801000
	s_addc_u32 s9, s67, 0
	v_and_b32_e32 v0, 63, v194
	v_mov_b32_e32 v11, 0
	v_and_b32_e32 v1, 15, v0
	v_lshlrev_b32_e32 v2, 3, v0
	v_add_u32_e32 v3, 0x1800, v2
	v_cmp_lt_u32_e32 vcc, 31, v0
	v_mov_b32_e32 v20, 0x1700
	s_nop 1
	v_cndmask_b32_e32 v20, 0, v20, vcc
	v_add_u32_e32 v4, v2, v20
	v_and_b32_e32 v21, 4, v1
	v_cmp_ne_u32_e32 vcc, 0, v21
	v_mov_b32_e32 v22, 1.0
	v_mov_b32_e32 v5, -1.0
	v_cndmask_b32_e32 v5, v5, v22, vcc
	v_mov_b32_e32 v6, 0x358637bd
	v_cmp_gt_u32_e32 vcc, 8, v1
	s_nop 1
	v_cndmask_b32_e64 v7, 0, 1, vcc
	v_mov_b32_e32 v22, 0x80
	v_cndmask_b32_e32 v8, v22, v11, vcc
	v_cmp_lt_u32_e32 vcc, 31, v0
	s_nop 1
	v_cndmask_b32_e32 v9, 0, v8, vcc
	v_and_b32_e32 v10, 3, v1
	v_lshlrev_b32_e32 v10, 5, v10
	global_load_dwordx4 v[24:27], v11, s[66:67] offset:152
	v_lshlrev_b32_e32 v20, 4, v1
	v_mov_b32_e32 v21, 0
	s_waitcnt vmcnt(0)
	v_lshl_add_u64 v[24:25], v[24:25], 0, v[20:21]
	v_lshl_add_u64 v[26:27], v[26:27], 0, v[20:21]
	global_load_dwordx4 v[12:15], v[24:25], off offset:256
	global_load_dwordx4 v[16:19], v[26:27], off offset:256

.Lprep_done_L1:
	s_mov_b64 s[42:43], s[66:67]
	s_mov_b64 s[0:1], s[68:69]
	s_waitcnt lgkmcnt(0)
	v_mov_b32_e32 v0, v194
	s_mov_b32 s54, s64
	s_and_b64 vcc, exec, s[4:5]
	s_barrier
	s_cbranch_vccnz .LBB0_2798
	v_ashrrev_i32_e32 v1, 6, v0
	v_mov_b32_e32 v43, 0
	v_bfe_u32 v5, v0, 4, 2
	s_movk_i32 s0, 0x1100
	v_lshlrev_b32_e32 v46, 4, v5
	v_mov_b32_e32 v47, v43
	v_lshlrev_b32_e32 v50, 4, v1
	v_mul_lo_u32 v4, v1, s0
	v_and_b32_e32 v41, 15, v0
	v_lshl_add_u64 v[2:3], s[42:43], 0, v[46:47]
	s_mov_b64 s[0:1], 0x10a00000
	v_ashrrev_i32_e32 v51, 31, v50
	v_lshl_add_u64 v[48:49], v[2:3], 0, s[0:1]
	v_lshl_add_u64 v[2:3], v[50:51], 1, s[42:43]
	v_lshlrev_b32_e32 v42, 1, v41
	s_add_u32 s44, s42, 0x5800000
	v_and_b32_e32 v40, 0x7f, v0
	v_lshl_add_u64 v[2:3], v[2:3], 0, v[42:43]
	s_mov_b64 s[0:1], 0xe800000
	s_addc_u32 s45, s43, 0
	v_ashrrev_i32_e32 v6, 7, v0
	v_lshl_add_u64 v[52:53], v[2:3], 0, s[0:1]
	s_add_i32 s0, 0, 0x1f000
	v_lshlrev_b32_e32 v2, 2, v40
	s_add_i32 s10, 0, 0x11800
	s_movk_i32 s19, 0x880
	v_lshlrev_b32_e32 v45, 4, v6
	v_lshl_add_u32 v47, v0, 2, s0
	v_add_u32_e32 v55, s0, v2
	s_movk_i32 s0, 0x80
	v_mul_u32_u24_e32 v87, 0x110, v41
	s_add_i32 s18, 0, 0x11a00
	v_add_u32_e32 v89, s10, v2
	v_mul_lo_u32 v2, v6, s19
	v_cmp_gt_u32_e64 s[8:9], s0, v0
	s_movk_i32 s0, 0x110
	v_add3_u32 v88, 0, v4, v87
	v_or_b32_e32 v4, v45, v41
	v_add_u32_e32 v54, s18, v46
	v_or_b32_e32 v2, v2, v40
	v_mad_u64_u32 v[56:57], s[0:1], v4, s0, v[54:55]
	v_lshlrev_b32_e32 v2, 1, v2
	s_add_i32 s0, 0, 0x15e00
	v_add_u32_e32 v8, 0x110, v2
	v_add_u32_e32 v92, s18, v8
	v_add_u32_e32 v93, s0, v8
	v_add_u32_e32 v8, 0x220, v2
	v_add_u32_e32 v94, s18, v8
	v_add_u32_e32 v95, s0, v8
	v_add_u32_e32 v8, 0x330, v2
	v_add_u32_e32 v96, s18, v8
	v_add_u32_e32 v97, s0, v8
	v_add_u32_e32 v8, 0x440, v2
	v_add_u32_e32 v98, s18, v8
	v_add_u32_e32 v99, s0, v8
	v_add_u32_e32 v8, 0x550, v2
	v_add_u32_e32 v100, s18, v8
	v_add_u32_e32 v101, s0, v8
	v_add_u32_e32 v8, 0x660, v2
	v_add_u32_e32 v102, s18, v8
	v_add_u32_e32 v103, s0, v8
	v_add_u32_e32 v8, 0x770, v2
	v_add_u32_e32 v104, s18, v8
	v_add_u32_e32 v105, s0, v8
	v_add_u32_e32 v8, 0x880, v2
	v_add_u32_e32 v106, s18, v8
	v_add_u32_e32 v107, s0, v8
	v_add_u32_e32 v8, 0x990, v2
	v_add_u32_e32 v108, s18, v8
	v_add_u32_e32 v109, s0, v8
	v_add_u32_e32 v8, 0xaa0, v2
	v_add_u32_e32 v110, s18, v8
	v_add_u32_e32 v111, s0, v8
	v_add_u32_e32 v8, 0xbb0, v2
	v_add_u32_e32 v112, s18, v8
	v_add_u32_e32 v113, s0, v8
	v_add_u32_e32 v8, 0xcc0, v2
	v_mul_u32_u24_e32 v0, 0x48, v40
	v_lshlrev_b32_e32 v1, 1, v1
	v_add_u32_e32 v114, s18, v8
	v_add_u32_e32 v115, s0, v8
	v_add_u32_e32 v8, 0xdd0, v2
	v_lshlrev_b32_e32 v44, 2, v5
	v_lshlrev_b32_e32 v0, 1, v0
	v_lshlrev_b32_e32 v3, 5, v6
	v_and_b32_e32 v1, 2, v1
	v_add_u32_e32 v90, s18, v2
	v_add_u32_e32 v91, s0, v2
	v_add_u32_e32 v116, s18, v8
	v_add_u32_e32 v117, s0, v8
	v_add_u32_e32 v8, 0xee0, v2
	v_add_u32_e32 v2, 0xff0, v2
	v_add3_u32 v86, 0, v0, v3
	v_or_b32_e32 v3, v44, v45
	v_add_u32_e32 v120, s18, v2
	v_add_u32_e32 v121, s0, v2
	v_lshl_or_b32 v2, v1, 4, v41
	v_lshlrev_b32_e32 v0, 3, v5
	v_or_b32_e32 v5, v50, v41
	s_movk_i32 s1, 0x90
	s_add_i32 s34, 0, 0x1a200
	v_add_u32_e32 v118, s18, v8
	v_cmp_le_i32_e64 s[18:19], v1, v6
	v_or_b32_e32 v10, 1, v3
	v_or_b32_e32 v11, 2, v3
	v_or_b32_e32 v12, 3, v3
	v_cmp_lt_i32_e64 s[20:21], v1, v6
	v_or_b32_e32 v1, 16, v2
	v_mul_lo_u32 v5, v5, s1
	v_add_u32_e32 v119, s0, v8
	v_mul_u32_u24_e32 v8, 0x110, v2
	v_mul_lo_u32 v9, v3, s1
	v_or_b32_e32 v13, 16, v41
	v_lshl_add_u32 v14, v2, 1, s34
	v_cmp_gt_i32_e64 s[22:23], v2, v3
	v_cmp_gt_i32_e64 s[24:25], v2, v10
	v_cmp_gt_i32_e64 s[26:27], v2, v11
	v_cmp_gt_i32_e64 s[28:29], v2, v12
	v_lshlrev_b32_e32 v2, 1, v1
	v_add_u32_e32 v4, s0, v46
	v_add_u32_e32 v5, 0, v5
	v_add_u32_e32 v7, s34, v46
	v_add_u32_e32 v57, 0, v46
	v_cmp_lt_i32_e64 s[10:11], 0, v6
	v_cmp_lt_i32_e64 s[12:13], 1, v6
	v_cmp_lt_i32_e64 s[14:15], 2, v6
	v_cmp_lt_i32_e64 s[16:17], 3, v6
	v_mul_u32_u24_e32 v6, 0x90, v41
	v_mul_u32_u24_e32 v13, 0x110, v13
	v_add3_u32 v122, s34, v9, v2
	s_mov_b32 s49, 0
	v_cmp_gt_i32_e64 s[30:31], v1, v3
	v_cmp_gt_i32_e64 s[34:35], v1, v10
	v_add_u32_e32 v123, 0x90, v122
	v_cmp_gt_i32_e64 s[36:37], v1, v11
	v_add_u32_e32 v124, 0x120, v122
	v_cmp_gt_i32_e64 s[38:39], v1, v12
	v_add_u32_e32 v125, 0x1b0, v122
	v_sub_u32_e32 v126, 0, v44
	v_sub_u32_e32 v127, 0, v45
	s_movk_i32 s55, 0x1000
	s_movk_i32 s56, 0x2000
	s_movk_i32 s57, 0x3000
	s_movk_i32 s58, 0x4000
	s_movk_i32 s59, 0x5000
	s_movk_i32 s60, 0x6000
	s_movk_i32 s61, 0x7000
	s_mov_b32 s62, 0xc800000
	s_movk_i32 s63, 0x1800
	s_mov_b64 s[50:51], 0x1600
	s_mov_b32 s70, 0xffff0000
	s_mov_b32 s71, 0xbfb8aa3b
	s_mov_b32 s72, 0x800000
	s_mov_b32 s73, 0x3f317217
	s_mov_b32 s77, 0x7f800000
	s_movk_i32 s78, 0x7fff
	v_add_u32_e32 v128, v88, v0
	v_add_u32_e32 v129, v14, v9
	v_add_u32_e32 v130, v5, v46
	v_add_u32_e32 v131, v7, v6
	v_add_u32_e32 v132, v54, v13
	v_add_u32_e32 v133, v57, v6
	v_mov_b32_e32 v134, 0x41b17218
	v_mov_b32_e32 v135, 1
	v_add_u32_e32 v136, v4, v8
	s_mov_b32 s79, s2
	s_mov_b32 s80, s2
	s_branch .LBB0_2786
